# grid barrier: the XCD leader issues its L1 invalidate behind the cross-XCD arrival atomic instead of next to the L2 write-back (off the pre-release path)
# baseline (speedup 1.0000x reference)
; __device__ __forceinline__ unsigned xb_ld(unsigned* p)              { return __hip_atomic_load(p, __ATOMIC_RELAXED, __HIP_MEMORY_SCOPE_AGENT); }
; __device__ __forceinline__ unsigned xb_add(unsigned* p, unsigned v) { return __hip_atomic_fetch_add(p, v, __ATOMIC_RELAXED, __HIP_MEMORY_SCOPE_AGENT); }
; #define XB_SPIN(cond, bar) do { unsigned _sp = 0; while (cond) { __builtin_amdgcn_s_sleep(1); \
;     if ((++_sp & 255u) == 0u) { if (xb_ld(&(bar)[XB_TMO])) break; if (_sp > XB_SPIN_CAP) { atomicAdd(&(bar)[XB_TMO], 1u); break; } } } } while (0)
; __device__ __forceinline__ void xcd_barrier(const XcdBarrier& b) {
;     ...
;             const unsigned og = xb_add(&bar[XB_TOP], 1u);
;             const unsigned tg = og / nx;
;             if (og + 1u == (tg + 1u) * nx) xb_add(&bar[XB_TOPGEN], 1u);
;             else XB_SPIN(xb_ld(&bar[XB_TOPGEN]) == tg, bar);
;             __builtin_amdgcn_fence(__ATOMIC_ACQUIRE, "agent");
.LBB0_89:
	s_or_b64 exec, exec, s[4:5]
	buffer_inv sc1
	v_cvt_f32_u32_e32 v3, v0
	s_waitcnt vmcnt(0)
	v_readfirstlane_b32 s2, v2
	s_mov_b64 s[4:5], -1
	v_rcp_iflag_f32_e32 v3, v3
	v_add_u32_e32 v1, s2, v1
	v_add_u32_e32 v4, 1, v1
	v_readlane_b32 s2, v253, 2
	v_mul_f32_e32 v2, 0x4f7ffffe, v3
	v_cvt_u32_f32_e32 v2, v2
	v_sub_u32_e32 v3, 0, v0
	v_readlane_b32 s3, v253, 3
	v_mul_lo_u32 v3, v3, v2
	v_mul_hi_u32 v3, v2, v3
	v_add_u32_e32 v2, v2, v3
	v_mul_hi_u32 v2, v1, v2
	v_mul_lo_u32 v3, v2, v0
	v_sub_u32_e32 v1, v1, v3
	v_add_u32_e32 v5, 1, v2
	v_cmp_ge_u32_e32 vcc, v1, v0
	v_sub_u32_e32 v3, v1, v0
	s_nop 0
	v_cndmask_b32_e32 v2, v2, v5, vcc
	v_cndmask_b32_e32 v1, v1, v3, vcc
	v_add_u32_e32 v3, 1, v2
	v_cmp_ge_u32_e32 vcc, v1, v0
	s_nop 1
	v_cndmask_b32_e32 v2, v2, v3, vcc
	v_mul_lo_u32 v1, v0, v2
	v_add_u32_e32 v0, v1, v0
	v_cmp_ne_u32_e32 vcc, v4, v0
	v_mov_b32_e32 v5, v0
	v_mov_b64_e32 v[0:1], s[2:3]
	s_and_saveexec_b64 s[2:3], vcc
	s_cbranch_execz .LBB0_101
	v_readlane_b32 s4, v253, 0
	v_mov_b32_e32 v0, 0
	v_readlane_b32 s5, v253, 1
	s_mov_b64 s[6:7], 0
	s_nop 3
	global_load_dword v1, v0, s[4:5] sc1
	s_waitcnt vmcnt(0)
	v_cmp_gt_u32_e32 vcc, v5, v1
	s_and_saveexec_b64 s[4:5], vcc
	s_cbranch_execz .LBB0_100
	s_mov_b32 s15, 1
	s_branch .LBB0_93

; __device__ __forceinline__ unsigned xb_ld(unsigned* p)              { return __hip_atomic_load(p, __ATOMIC_RELAXED, __HIP_MEMORY_SCOPE_AGENT); }
; __device__ __forceinline__ unsigned xb_add(unsigned* p, unsigned v) { return __hip_atomic_fetch_add(p, v, __ATOMIC_RELAXED, __HIP_MEMORY_SCOPE_AGENT); }
; #define XB_SPIN(cond, bar) do { unsigned _sp = 0; while (cond) { __builtin_amdgcn_s_sleep(1); \
;     if ((++_sp & 255u) == 0u) { if (xb_ld(&(bar)[XB_TMO])) break; if (_sp > XB_SPIN_CAP) { atomicAdd(&(bar)[XB_TMO], 1u); break; } } } } while (0)
; __device__ __forceinline__ void xcd_barrier(const XcdBarrier& b) {
;     ...
;             const unsigned og = xb_add(&bar[XB_TOP], 1u);
;             const unsigned tg = og / nx;
;             if (og + 1u == (tg + 1u) * nx) xb_add(&bar[XB_TOPGEN], 1u);
;             else XB_SPIN(xb_ld(&bar[XB_TOPGEN]) == tg, bar);
;             __builtin_amdgcn_fence(__ATOMIC_ACQUIRE, "agent");
.LBB0_259:
	s_or_b64 exec, exec, s[24:25]
	buffer_inv sc1
	s_waitcnt vmcnt(0)
	v_readfirstlane_b32 s0, v2
	v_cvt_f32_u32_e32 v2, v0
	v_sub_u32_e32 v3, 0, v0
	v_add_u32_e32 v1, s0, v1
	v_readlane_b32 s12, v253, 2
	v_rcp_iflag_f32_e32 v2, v2
	v_readlane_b32 s13, v253, 3
	s_mov_b64 s[24:25], -1
	v_mul_f32_e32 v2, 0x4f7ffffe, v2
	v_cvt_u32_f32_e32 v2, v2
	v_mul_lo_u32 v3, v3, v2
	v_mul_hi_u32 v3, v2, v3
	v_add_u32_e32 v2, v2, v3
	v_mul_hi_u32 v2, v1, v2
	v_mul_lo_u32 v3, v2, v0
	v_sub_u32_e32 v3, v1, v3
	v_cmp_ge_u32_e32 vcc, v3, v0
	v_add_u32_e32 v4, 1, v2
	v_add_u32_e32 v1, 1, v1
	v_cndmask_b32_e32 v2, v2, v4, vcc
	v_sub_u32_e32 v4, v3, v0
	v_cndmask_b32_e32 v3, v3, v4, vcc
	v_cmp_ge_u32_e32 vcc, v3, v0
	v_add_u32_e32 v3, 1, v2
	s_nop 0
	v_cndmask_b32_e32 v2, v2, v3, vcc
	v_mul_lo_u32 v3, v0, v2
	v_add_u32_e32 v0, v3, v0
	v_cmp_ne_u32_e32 vcc, v1, v0
	v_mov_b32_e32 v5, v0
	v_mov_b64_e32 v[0:1], s[12:13]
	s_and_saveexec_b64 s[12:13], vcc
	s_cbranch_execz .LBB0_271
	v_readlane_b32 s24, v253, 0
	v_readlane_b32 s25, v253, 1
	s_mov_b64 s[26:27], 0
	s_nop 3
	global_load_dword v0, v185, s[24:25] sc1
	s_waitcnt vmcnt(0)
	v_cmp_gt_u32_e32 vcc, v5, v0
	s_and_saveexec_b64 s[24:25], vcc
	s_cbranch_execz .LBB0_270
	s_mov_b32 s0, 1
	s_branch .LBB0_263
